# phase-2 load balance: CUs that run a cmp1 GEMM tile keep 1 of 4 gdn_g1 chunks, other waves take one extra each; NSA fast path v2 (quick entry, packed f32 adds, coarse waits)
# speedup vs baseline: 1.0398x; 1.0074x over previous
.LBB0_267:
	s_ashr_i32 s0, s24, 6
	v_readlane_b32 s1, v253, 44
	s_add_i32 s1, s1, s0
	s_add_i32 s2, s1, 0x200
	s_sub_i32 s1, 0xfffffe00, s1
	s_max_i32 s1, s2, s1
	s_ashr_i32 s0, s2, 31
	s_mul_hi_u32 s2, s1, s57
	s_mul_i32 s2, s2, s56
	s_sub_i32 s1, s1, s2
	s_sub_i32 s2, s1, s56
	s_cmp_ge_u32 s1, s56
	s_cselect_b32 s1, s2, s1
	s_sub_i32 s2, s1, s56
	s_cmp_ge_u32 s1, s56
	s_cselect_b32 s1, s2, s1
	s_xor_b32 s1, s1, s0
	s_sub_i32 s4, s1, s0
	s_mov_b32 s98, -1
	s_cmpk_gt_i32 s4, 0x1fff
	s_cbranch_scc1 .LBB0_290
	v_lshlrev_b32_e32 v0, 2, v154
	v_and_b32_e32 v2, 60, v0
	v_mbcnt_hi_u32_b32 v0, -1, v230
	v_and_b32_e32 v1, 64, v0
	v_add_u32_e32 v1, 64, v1
	v_xor_b32_e32 v3, 1, v0
	v_cmp_lt_i32_e32 vcc, v3, v1
	v_lshlrev_b32_e32 v48, 1, v2
	v_mov_b32_e32 v49, 0
	v_cndmask_b32_e32 v3, v0, v3, vcc
	v_lshlrev_b32_e32 v201, 2, v3
	v_xor_b32_e32 v3, 2, v0
	v_cmp_lt_i32_e32 vcc, v3, v1
	v_bfe_u32 v200, v154, 4, 2
	v_lshl_add_u64 v[50:51], s[92:93], 0, v[48:49]
	v_cndmask_b32_e32 v3, v0, v3, vcc
	v_lshlrev_b32_e32 v202, 2, v3
	v_xor_b32_e32 v3, 4, v0
	v_cmp_lt_i32_e32 vcc, v3, v1
	v_lshlrev_b32_e32 v48, 2, v2
	s_lshl_b32 s1, s1, 6
	v_cndmask_b32_e32 v3, v0, v3, vcc
	v_lshlrev_b32_e32 v203, 2, v3
	v_xor_b32_e32 v3, 8, v0
	v_cmp_lt_i32_e32 vcc, v3, v1
	s_lshl_b32 s0, s0, 6
	s_ashr_i32 s5, s4, 31
	v_cndmask_b32_e32 v0, v0, v3, vcc
	v_lshlrev_b32_e32 v204, 2, v0
	v_lshlrev_b32_e32 v0, 3, v154
	v_lshl_add_u64 v[52:53], s[18:19], 0, v[48:49]
	s_sub_i32 s9, s1, s0
	v_and_b32_e32 v48, 0x78, v0
	s_lshl_b64 s[0:1], s[4:5], 13
	v_lshlrev_b32_e32 v0, 7, v200
	v_or3_b32 v56, s0, v0, v48
	v_mov_b32_e32 v57, s1
	v_lshl_add_u64 v[0:1], s[46:47], 0, v[48:49]
	s_mov_b64 s[0:1], 0x29b00200
	v_lshlrev_b32_e32 v205, 6, v200
	v_lshl_add_u64 v[58:59], v[0:1], 0, s[0:1]
	s_lshl_b64 s[0:1], s[4:5], 12
	s_ashr_i32 s87, s86, 31
	v_or3_b32 v0, s0, v205, v2
	v_mov_b32_e32 v1, s1
	v_or_b32_e32 v206, 0x300, v205
	s_lshl_b32 s24, s88, 9
	v_or_b32_e32 v54, 0x11b00000, v48
	v_mov_b32_e32 v55, v49
	v_or_b32_e32 v207, 12, v200
	v_add_u32_e32 v208, 11, v200
	v_add_u32_e32 v209, 10, v200
	v_add_u32_e32 v212, 9, v200
	s_lshl_b64 s[6:7], s[86:87], 13
	v_or_b32_e32 v213, 0x200, v205
	v_or_b32_e32 v214, 8, v200
	v_add_u32_e32 v215, 7, v200
	v_add_u32_e32 v216, 6, v200
	v_add_u32_e32 v217, 5, v200
	v_or_b32_e32 v218, 0x100, v205
	v_or_b32_e32 v219, 4, v200
	v_add_u32_e32 v220, 3, v200
	v_add_u32_e32 v221, 2, v200
	v_add_u32_e32 v222, 1, v200
	v_lshlrev_b64 v[60:61], 1, v[0:1]
	s_movk_i32 s5, 0x1000
	s_movk_i32 s28, 0x3000
	s_movk_i32 s29, 0x4000
	s_movk_i32 s30, 0x2000
	s_movk_i32 s31, 0x5000
	s_brev_b32 s33, 23
	s_mov_b32 s8, 0x358637bd
	s_mov_b32 s34, 0x800000
	s_mov_b32 s35, 0x29b00000
	s_mov_b32 s36, 0x2db00000
	s_mov_b32 s37, 0x31b00000
	s_mov_b64 s[12:13], 0x1000
	s_mov_b64 s[14:15], 0x800
	s_movk_i32 s99, 0x1fff
	s_cmp_lt_u32 s94, 64
	s_cbranch_scc0 .Lg1_bal_b
	s_movk_i32 s99, 0x7ff
	s_branch .LBB0_270
.Lg1_bal_b:
	v_readfirstlane_b32 s100, v210
	s_lshr_b32 s100, s100, 6
	s_lshl_b32 s101, s94, 3
	s_add_i32 s100, s100, s101
	s_sub_i32 s100, s100, 0x200
	s_mul_hi_u32 s101, s100, 0xaaaaaaab
	s_lshr_b32 s101, s101, 1
	s_mul_i32 s98, s101, 3
	s_sub_i32 s98, s100, s98
	s_mul_i32 s98, s98, 0x800
	s_sub_i32 s98, 0x1a00, s98
	s_add_i32 s98, s98, s101
	s_branch .LBB0_270
.LBB0_269:
	s_add_i32 s4, s4, s86
	s_add_i32 s9, s9, s24
	v_lshl_add_u64 v[56:57], v[56:57], 0, s[6:7]
	s_cmp_gt_i32 s4, s99
	v_lshl_add_u64 v[60:61], v[60:61], 0, s[6:7]
	s_cbranch_scc1 .LBB0_290

.LBB0_290:
	s_cmp_lt_i32 s98, 0
	s_cbranch_scc1 .Lg1_noextra
	s_sub_i32 s100, s98, s4
	s_mov_b32 s4, s98
	s_mov_b32 s99, s98
	s_mov_b32 s98, -1
	s_lshl_b32 s101, s100, 6
	s_add_i32 s9, s9, s101
	s_ashr_i32 s101, s100, 31
	s_lshl_b64 s[100:101], s[100:101], 13
	v_lshl_add_u64 v[56:57], v[56:57], 0, s[100:101]
	v_lshl_add_u64 v[60:61], v[60:61], 0, s[100:101]
	s_branch .LBB0_270

.LBB0_581:
	s_or_b64 exec, exec, s[2:3]
	s_lshl_b32 s0, s15, 3
	v_readlane_b32 s1, v254, 9
	v_mul_f32_e32 v32, 0xbfb8aa3b, v72
	s_add_i32 s0, s1, s0
	v_and_b32_e32 v33, 31, v75
	v_exp_f32_e32 v34, v32
	v_lshl_add_u32 v32, v88, 3, s0
	v_lshl_add_u32 v33, v33, 3, s1
	s_waitcnt lgkmcnt(0)
	s_barrier
	ds_read_b64 v[60:61], v32
	ds_read_b64 v[32:33], v33
	v_mul_f32_e32 v35, 0xbfb8aa3b, v74
	v_exp_f32_e32 v35, v35
	v_lshlrev_b64 v[68:69], 16, v[82:83]
	v_add_f32_e32 v34, 1.0, v34
	s_waitcnt lgkmcnt(0)
	ds_bpermute_b32 v40, v108, v33
	ds_bpermute_b32 v41, v108, v32
	v_add_f32_e32 v35, 1.0, v35
	v_rcp_f32_e32 v83, v35
	v_xor_b32_e32 v35, 8, v174
	v_cmp_lt_i32_e32 vcc, v35, v116
	s_waitcnt lgkmcnt(1)
	v_or_b32_e32 v33, v40, v33
	s_waitcnt lgkmcnt(0)
	v_or_b32_e32 v32, v41, v32
	v_cndmask_b32_e32 v35, v174, v35, vcc
	v_lshlrev_b32_e32 v35, 2, v35
	ds_bpermute_b32 v40, v35, v33
	ds_bpermute_b32 v35, v35, v32
	v_rcp_f32_e32 v34, v34
	s_lshr_b32 s55, s14, 6
	s_lshl_b64 s[0:1], 2, s55
	s_add_u32 s0, s0, -1
	s_waitcnt lgkmcnt(0)
	v_pk_fma_f32 v[74:75], v[34:35], v[28:29], 0 op_sel_hi:[0,1,0]
	v_xor_b32_e32 v28, 4, v174
	v_cmp_lt_i32_e32 vcc, v28, v116
	v_pk_fma_f32 v[58:59], v[34:35], v[26:27], 0 op_sel_hi:[0,1,0]
	v_or_b32_e32 v26, v40, v33
	v_cndmask_b32_e32 v28, v174, v28, vcc
	v_or_b32_e32 v27, v35, v32
	v_lshlrev_b32_e32 v28, 2, v28
	ds_bpermute_b32 v29, v28, v26
	ds_bpermute_b32 v28, v28, v27
	v_pk_fma_f32 v[64:65], v[34:35], v[20:21], 0 op_sel_hi:[0,1,0]
	v_pk_fma_f32 v[62:63], v[34:35], v[22:23], 0 op_sel_hi:[0,1,0]
	s_addc_u32 s1, s1, -1
	s_waitcnt lgkmcnt(1)
	v_or_b32_e32 v20, v29, v26
	s_waitcnt lgkmcnt(0)
	v_or_b32_e32 v21, v28, v27
	ds_bpermute_b32 v22, v37, v20
	ds_bpermute_b32 v23, v37, v21
	s_cmp_lg_u32 s55, 63
	v_pk_fma_f32 v[56:57], v[34:35], v[18:19], 0 op_sel_hi:[0,1,0]
	v_mul_f32_e32 v18, 0xbfb8aa3b, v73
	s_cselect_b32 s1, s1, -1
	s_cselect_b32 s0, s0, -1
	s_lshl_b32 s2, s10, 1
	v_exp_f32_e32 v18, v18
	s_waitcnt lgkmcnt(1)
	v_or_b32_e32 v19, v22, v20
	s_waitcnt lgkmcnt(0)
	v_or_b32_e32 v20, v23, v21
	s_add_u32 s58, s92, s2
	ds_bpermute_b32 v21, v36, v19
	ds_bpermute_b32 v22, v36, v20
	s_addc_u32 s59, s93, 0
	v_readlane_b32 s2, v253, 61
	v_readlane_b32 s3, v253, 62
	s_add_u32 s60, s2, s11
	v_readlane_b32 s2, v254, 32
	s_addc_u32 s61, s3, 0
	s_sub_i32 s2, 0xde0, s2
	v_pk_fma_f32 v[70:71], v[34:35], v[16:17], 0 op_sel_hi:[0,1,0]
	v_add_f32_e32 v16, 1.0, v18
	s_ashr_i32 s2, s2, 6
	v_mul_u32_u24_e32 v113, 0x90, v114
	v_rcp_f32_e32 v114, v16
	s_cmpk_gt_i32 s14, 0x1fe
	s_waitcnt lgkmcnt(1)
	v_or_b32_e32 v16, v21, v19
	s_waitcnt lgkmcnt(0)
	v_or_b32_e32 v17, v22, v20
	s_cselect_b32 s2, s2, 0
	v_and_b32_e32 v16, s1, v16
	v_and_b32_e32 v17, s0, v17
	s_lshl_b64 s[2:3], -1, s2
	v_add3_u32 v116, 0, v89, v76
	v_mul_u32_u24_e32 v110, 0x90, v110
	v_mul_u32_u24_e32 v111, 0x90, v111
	v_mul_u32_u24_e32 v112, 0x90, v112
	v_pk_fma_f32 v[66:67], v[34:35], v[30:31], 0 op_sel_hi:[0,1,0]
	v_pk_fma_f32 v[86:87], v[34:35], v[24:25], 0 op_sel_hi:[0,1,0]
	v_readfirstlane_b32 s56, v16
	v_readfirstlane_b32 s57, v17
	s_and_b64 s[34:35], s[0:1], s[2:3]
	v_lshl_add_u32 v117, v90, 1, v116
	s_add_i32 s62, s54, 0xfffffe03
	v_add_u32_e32 v118, 0xfffffe00, v78
	v_mul_u32_u24_e32 v119, 0x90, v38
	v_mul_u32_u24_e32 v120, 0x90, v39
	v_and_b32_e32 v211, 1, v210
	v_lshlrev_b32_e32 v211, 5, v211
	v_sub_u32_e32 v211, 16, v211
	v_lshrrev_b32_e32 v228, 1, v82
	v_xor_b32_e32 v228, v228, v82
	v_bfe_u32 v229, v228, 3, 1
	v_bfe_u32 v228, v228, 2, 1
	v_mad_i32_i24 v117, v229, v211, v117
	v_mad_i32_i24 v116, v228, v211, v116
	v_lshrrev_b32_e32 v228, 1, v210
	v_xor_b32_e32 v228, v228, v210
	v_bfe_u32 v228, v228, 2, 1
	v_lshlrev_b32_e32 v228, 4, v228
	v_xor_b32_e32 v208, v103, v228
	v_xor_b32_e32 v209, v115, v228
	v_add3_u32 v175, v110, v79, v208
	v_add3_u32 v211, v111, v79, v208
	v_add3_u32 v228, v112, v104, v208
	v_add3_u32 v229, v113, v104, v208
	v_add_u32_e32 v231, v209, v119
	v_add_u32_e32 v252, v209, v120
	s_mov_b64 s[36:37], 0
	s_mov_b64 s[38:39], -1
	s_branch .LBB0_583

.LBB0_589:
	s_cmp_lt_u32 s4, s55
	s_cbranch_scc0 .Lnsa_diag
	v_lshrrev_b64 v[40:41], s4, v[60:61]
	v_and_b32_e32 v40, 1, v40
	v_cmp_eq_u32_e64 s[6:7], 1, v40
	s_cmp_eq_u64 s[6:7], 0
	s_cbranch_scc1 .LBB0_593
	s_branch .Lnsa_fastq

.LBB0_602:
	s_mov_b32 s0, 0xffff
	v_cmp_ne_u32_e32 vcc, s0, v127
	s_and_b64 s[0:1], s[6:7], vcc
	v_cndmask_b32_e64 v40, 0, 1, s[0:1]
	s_mul_i32 s0, s63, 0x2500
	s_add_i32 s0, s0, 0
	v_cmp_ne_u32_e32 vcc, 0, v40
	v_add_u32_e32 v40, s0, v110
	v_add_u32_e32 v41, s0, v111
	v_add_u32_e32 v42, s0, v112
	v_add_u32_e32 v43, s0, v113
	s_mul_i32 s0, s63, 0x2400
	v_add3_u32 v126, v40, v79, v208
	v_add3_u32 v125, v41, v79, v208
	v_add3_u32 v124, v42, v104, v208
	v_add3_u32 v90, v43, v104, v208
	v_add_u32_e32 v123, s0, v209
	s_cbranch_vccz .Lnsa_fast
	ds_read_b128 v[40:43], v126
	ds_read_b128 v[44:47], v126 offset:64
	v_add_u32_e32 v146, v123, v120
	s_waitcnt lgkmcnt(1)
	v_mfma_f32_16x16x32_bf16 v[40:43], v[40:43], v[4:7], 0
	ds_read_b128 v[128:131], v90 offset:64
	s_waitcnt lgkmcnt(1)
	v_mfma_f32_16x16x32_bf16 v[52:55], v[44:47], v[0:3], v[40:43]
	ds_read_b128 v[44:47], v125 offset:64
	s_nop 3
	ds_read_b128 v[40:43], v125
	s_waitcnt lgkmcnt(0)
	v_mfma_f32_16x16x32_bf16 v[40:43], v[40:43], v[4:7], 0
	v_mfma_f32_16x16x32_bf16 v[48:51], v[44:47], v[0:3], v[40:43]
	ds_read_b128 v[44:47], v124 offset:64
	s_nop 5
	ds_read_b128 v[40:43], v124
	s_waitcnt lgkmcnt(0)
	v_mfma_f32_16x16x32_bf16 v[40:43], v[40:43], v[4:7], 0
	v_mfma_f32_16x16x32_bf16 v[44:47], v[44:47], v[0:3], v[40:43]
	s_nop 6
	ds_read_b128 v[40:43], v90
	s_waitcnt lgkmcnt(0)
	v_mfma_f32_16x16x32_bf16 v[40:43], v[40:43], v[4:7], 0
	v_mfma_f32_16x16x32_bf16 v[40:43], v[128:131], v[0:3], v[40:43]
	v_and_b32_e32 v128, 1, v127
	v_cmp_eq_u32_e32 vcc, 0, v128
	v_max_f32_e32 v128, v52, v52
	v_max_f32_e32 v128, 0xf149f2ca, v128
	v_and_b32_e32 v129, 2, v127
	v_cndmask_b32_e32 v128, v128, v92, vcc
	v_cmp_eq_u32_e64 s[10:11], 0, v129
	v_max_f32_e32 v129, v53, v53
	v_max_f32_e32 v129, v128, v129
	v_cndmask_b32_e64 v128, v129, v128, s[10:11]
	v_and_b32_e32 v129, 4, v127
	v_cmp_eq_u32_e64 s[26:27], 0, v129
	v_max_f32_e32 v129, v54, v54
	v_max_f32_e32 v129, v128, v129
	v_cndmask_b32_e64 v128, v129, v128, s[26:27]
	v_and_b32_e32 v129, 8, v127
	v_cmp_eq_u32_e64 s[30:31], 0, v129
	v_max_f32_e32 v129, v55, v55
	v_max_f32_e32 v129, v128, v129
	v_cndmask_b32_e64 v128, v129, v128, s[30:31]
	v_and_b32_e32 v129, 16, v127
	v_cmp_eq_u32_e64 s[24:25], 0, v129
	v_max_f32_e32 v129, v48, v48
	v_max_f32_e32 v129, v128, v129
	v_cndmask_b32_e64 v128, v129, v128, s[24:25]
	v_and_b32_e32 v129, 32, v127
	v_cmp_eq_u32_e64 s[28:29], 0, v129
	v_max_f32_e32 v129, v128, v128
	v_max_f32_e32 v130, v49, v49
	v_max_f32_e32 v129, v129, v130
	v_cndmask_b32_e64 v128, v129, v128, s[28:29]
	v_and_b32_e32 v129, 64, v127
	v_cmp_eq_u32_e64 s[18:19], 0, v129
	v_max_f32_e32 v129, v128, v128
	v_max_f32_e32 v130, v50, v50
	v_max_f32_e32 v129, v129, v130
	v_cndmask_b32_e64 v128, v129, v128, s[18:19]
	v_and_b32_e32 v129, 0x80, v127
	v_cmp_eq_u32_e64 s[20:21], 0, v129
	v_max_f32_e32 v129, v128, v128
	v_max_f32_e32 v130, v51, v51
	v_max_f32_e32 v129, v129, v130
	v_cndmask_b32_e64 v128, v129, v128, s[20:21]
	v_and_b32_e32 v129, 0x100, v127
	v_cmp_eq_u32_e64 s[22:23], 0, v129
	v_max_f32_e32 v129, v128, v128
	v_max_f32_e32 v130, v44, v44
	v_max_f32_e32 v129, v129, v130
	v_cndmask_b32_e64 v128, v129, v128, s[22:23]
	v_and_b32_e32 v129, 0x200, v127
	v_cmp_eq_u32_e64 s[8:9], 0, v129
	v_max_f32_e32 v129, v128, v128
	v_max_f32_e32 v130, v45, v45
	v_max_f32_e32 v129, v129, v130
	v_cndmask_b32_e64 v128, v129, v128, s[8:9]
	v_and_b32_e32 v129, 0x400, v127
	v_cmp_eq_u32_e64 s[12:13], 0, v129
	v_max_f32_e32 v129, v128, v128
	v_max_f32_e32 v130, v46, v46
	v_max_f32_e32 v129, v129, v130
	v_cndmask_b32_e64 v128, v129, v128, s[12:13]
	v_and_b32_e32 v129, 0x800, v127
	v_cmp_eq_u32_e64 s[14:15], 0, v129
	v_max_f32_e32 v129, v128, v128
	v_max_f32_e32 v130, v47, v47
	v_max_f32_e32 v129, v129, v130
	v_cndmask_b32_e64 v128, v129, v128, s[14:15]
	v_and_b32_e32 v129, 0x1000, v127
	v_cmp_eq_u32_e64 s[16:17], 0, v129
	v_max_f32_e32 v129, v128, v128
	v_max_f32_e32 v130, v40, v40
	v_max_f32_e32 v129, v129, v130
	v_cndmask_b32_e64 v128, v129, v128, s[16:17]
	v_and_b32_e32 v129, 0x2000, v127
	v_cmp_eq_u32_e64 s[0:1], 0, v129
	v_max_f32_e32 v129, v128, v128
	v_max_f32_e32 v130, v41, v41
	v_max_f32_e32 v129, v129, v130
	v_cndmask_b32_e64 v128, v129, v128, s[0:1]
	v_and_b32_e32 v129, 0x4000, v127
	v_cmp_eq_u32_e64 s[2:3], 0, v129
	v_max_f32_e32 v129, v128, v128
	v_max_f32_e32 v130, v42, v42
	v_max_f32_e32 v129, v129, v130
	v_cndmask_b32_e64 v128, v129, v128, s[2:3]
	v_and_b32_e32 v127, 0x8000, v127
	v_cmp_eq_u32_e64 s[4:5], 0, v127
	v_max_f32_e32 v127, v128, v128
	v_max_f32_e32 v129, v43, v43
	v_max_f32_e32 v127, v127, v129
	v_cndmask_b32_e64 v127, v127, v128, s[4:5]
	v_mov_b32_e32 v128, v127
	s_nop 1
	v_permlane16_swap_b32_e32 v128, v127
	v_max_f32_e32 v127, v127, v128
	v_mov_b32_e32 v128, v127
	s_nop 1
	v_permlane32_swap_b32_e32 v128, v127
	v_max3_f32 v127, v122, v127, v128
	v_sub_f32_e32 v53, v53, v127
	v_exp_f32_e32 v53, v53
	v_sub_f32_e32 v49, v49, v127
	v_exp_f32_e32 v49, v49
	v_sub_f32_e32 v52, v52, v127
	v_cndmask_b32_e64 v131, v53, 0, s[10:11]
	v_sub_f32_e32 v53, v54, v127
	v_exp_f32_e32 v53, v53
	v_exp_f32_e32 v52, v52
	v_sub_f32_e32 v45, v45, v127
	v_cndmask_b32_e64 v135, v49, 0, s[28:29]
	v_sub_f32_e32 v49, v50, v127
	v_exp_f32_e32 v45, v45
	v_cndmask_b32_e64 v132, v53, 0, s[26:27]
	v_sub_f32_e32 v53, v55, v127
	v_exp_f32_e32 v49, v49
	v_exp_f32_e32 v53, v53
	v_sub_f32_e32 v48, v48, v127
	v_cndmask_b32_e64 v130, v52, 0, vcc
	v_exp_f32_e32 v48, v48
	v_sub_f32_e32 v41, v41, v127
	v_add_f32_e32 v52, 0, v130
	v_cndmask_b32_e64 v139, v45, 0, s[8:9]
	v_sub_f32_e32 v45, v46, v127
	v_exp_f32_e32 v41, v41
	v_add_f32_e32 v52, v131, v52
	v_cndmask_b32_e64 v136, v49, 0, s[18:19]
	v_sub_f32_e32 v49, v51, v127
	v_exp_f32_e32 v45, v45
	v_add_f32_e32 v52, v132, v52
	v_cndmask_b32_e64 v133, v53, 0, s[30:31]
	v_exp_f32_e32 v49, v49
	v_sub_f32_e32 v44, v44, v127
	v_add_f32_e32 v52, v133, v52
	v_cndmask_b32_e64 v134, v48, 0, s[24:25]
	v_exp_f32_e32 v44, v44
	v_add_f32_e32 v48, v134, v52
	v_cndmask_b32_e64 v143, v41, 0, s[0:1]
	v_sub_f32_e32 v41, v42, v127
	v_sub_f32_e32 v129, v122, v127
	v_add_f32_e32 v48, v135, v48
	v_cndmask_b32_e64 v140, v45, 0, s[12:13]
	v_sub_f32_e32 v45, v47, v127
	v_exp_f32_e32 v41, v41
	v_add_f32_e32 v48, v136, v48
	v_cndmask_b32_e64 v137, v49, 0, s[20:21]
	v_exp_f32_e32 v45, v45
	v_sub_f32_e32 v40, v40, v127
	v_exp_f32_e32 v52, v129
	v_add_u32_e32 v129, v123, v119
	v_add_f32_e32 v48, v137, v48
	v_cndmask_b32_e64 v138, v44, 0, s[22:23]
	v_exp_f32_e32 v40, v40
	v_cvt_pk_bf16_f32 v130, v130, v131
	v_cvt_pk_bf16_f32 v131, v132, v133
	v_cvt_pk_bf16_f32 v132, v134, v135
	v_cvt_pk_bf16_f32 v133, v136, v137
	ds_read_b128 v[134:137], v129 offset:38912
	v_add_f32_e32 v44, v138, v48
	v_add_f32_e32 v44, v139, v44
	v_cndmask_b32_e64 v144, v41, 0, s[2:3]
	v_sub_f32_e32 v41, v43, v127
	v_add_f32_e32 v44, v140, v44
	v_cndmask_b32_e64 v141, v45, 0, s[14:15]
	v_exp_f32_e32 v41, v41
	v_add_f32_e32 v44, v141, v44
	v_cndmask_b32_e64 v142, v40, 0, s[16:17]
	v_add_f32_e32 v40, v142, v44
	v_add_f32_e32 v40, v143, v40
	v_add_f32_e32 v40, v144, v40
	v_cndmask_b32_e64 v145, v41, 0, s[4:5]
	v_add_f32_e32 v128, v145, v40
	v_pk_mul_f32 v[42:43], v[38:39], v[52:53] op_sel_hi:[1,0]
	v_pk_mul_f32 v[40:41], v[36:37], v[52:53] op_sel_hi:[1,0]
	v_pk_mul_f32 v[46:47], v[34:35], v[52:53] op_sel_hi:[1,0]
	v_pk_mul_f32 v[44:45], v[32:33], v[52:53] op_sel_hi:[1,0]
	s_waitcnt lgkmcnt(0)
	v_mfma_f32_16x16x32_bf16 v[40:43], v[134:137], v[130:133], v[40:43]
	ds_read_b128 v[134:137], v129 offset:41216
	v_pk_mul_f32 v[50:51], v[30:31], v[52:53] op_sel_hi:[1,0]
	v_pk_mul_f32 v[48:49], v[28:29], v[52:53] op_sel_hi:[1,0]
	s_waitcnt lgkmcnt(0)
	v_mfma_f32_16x16x32_bf16 v[44:47], v[134:137], v[130:133], v[44:47]
	ds_read_b128 v[134:137], v129 offset:43520
	v_fmac_f32_e32 v128, v121, v52
	v_pk_mul_f32 v[54:55], v[26:27], v[52:53] op_sel_hi:[1,0]
	s_waitcnt lgkmcnt(0)
	v_mfma_f32_16x16x32_bf16 v[48:51], v[134:137], v[130:133], v[48:51]
	ds_read_b128 v[134:137], v146 offset:38912
	v_pk_mul_f32 v[52:53], v[24:25], v[52:53] op_sel_hi:[1,0]
	s_waitcnt lgkmcnt(0)
	s_nop 0
	v_mfma_f32_16x16x32_bf16 v[52:55], v[134:137], v[130:133], v[52:55]
	v_cvt_pk_bf16_f32 v130, v138, v139
	v_cvt_pk_bf16_f32 v131, v140, v141
	v_cvt_pk_bf16_f32 v132, v142, v143
	v_cvt_pk_bf16_f32 v133, v144, v145
	ds_read_b128 v[134:137], v129 offset:38976
	s_waitcnt lgkmcnt(0)
	v_mfma_f32_16x16x32_bf16 v[40:43], v[134:137], v[130:133], v[40:43]
	ds_read_b128 v[134:137], v129 offset:41280
	s_waitcnt lgkmcnt(0)
	v_mfma_f32_16x16x32_bf16 v[44:47], v[134:137], v[130:133], v[44:47]
	ds_read_b128 v[134:137], v129 offset:43584
	s_waitcnt lgkmcnt(0)
	v_mfma_f32_16x16x32_bf16 v[48:51], v[134:137], v[130:133], v[48:51]
	ds_read_b128 v[134:137], v146 offset:38976
	s_waitcnt lgkmcnt(0)
	v_mfma_f32_16x16x32_bf16 v[52:55], v[134:137], v[130:133], v[52:55]
	s_branch .LBB0_608
.Lnsa_fastq_all:
	s_mov_b64 s[6:7], -1
.Lnsa_fastq:
	s_mul_i32 s0, s63, 0x2500
	s_mul_i32 s1, s63, 0x2400
	v_add_u32_e32 v126, s0, v175
	v_add_u32_e32 v125, s0, v211
	v_add_u32_e32 v124, s0, v228
	v_add_u32_e32 v90, s0, v229
	v_add_u32_e32 v172, s1, v231
	v_add_u32_e32 v173, s1, v252
	ds_read_b128 v[176:179], v126
	ds_read_b128 v[180:183], v125
	ds_read_b128 v[184:187], v124
	ds_read_b128 v[188:191], v90
	ds_read_b128 v[192:195], v126 offset:64
	ds_read_b128 v[196:199], v125 offset:64
	ds_read_b128 v[200:203], v124 offset:64
	ds_read_b128 v[204:207], v90 offset:64
	v_cndmask_b32_e64 v168, v102, 0, s[6:7]
	v_mov_b32_e32 v169, v168
	v_mov_b32_e32 v170, v168
	v_mov_b32_e32 v171, v168
	ds_read_b128 v[212:215], v172 offset:38912
	ds_read_b128 v[216:219], v172 offset:41216
	ds_read_b128 v[220:223], v172 offset:43520
	ds_read_b128 v[224:227], v173 offset:38912
	ds_read_b128 v[232:235], v172 offset:38976
	ds_read_b128 v[236:239], v172 offset:41280
	s_waitcnt lgkmcnt(10)
	v_mfma_f32_16x16x32_bf16 v[52:55], v[176:179], v[4:7], v[168:171]
	v_mfma_f32_16x16x32_bf16 v[48:51], v[180:183], v[4:7], v[168:171]
	ds_read_b128 v[240:243], v172 offset:43584
	v_mfma_f32_16x16x32_bf16 v[44:47], v[184:187], v[4:7], v[168:171]
	ds_read_b128 v[244:247], v173 offset:38976
	v_mfma_f32_16x16x32_bf16 v[40:43], v[188:191], v[4:7], v[168:171]
	s_waitcnt lgkmcnt(8)
	v_mfma_f32_16x16x32_bf16 v[52:55], v[192:195], v[0:3], v[52:55]
	v_mfma_f32_16x16x32_bf16 v[48:51], v[196:199], v[0:3], v[48:51]
	v_mfma_f32_16x16x32_bf16 v[44:47], v[200:203], v[0:3], v[44:47]
	v_mfma_f32_16x16x32_bf16 v[40:43], v[204:207], v[0:3], v[40:43]
	s_nop 4
	v_max3_f32 v90, v52, v53, v54
	v_max3_f32 v90, v90, v55, v48
	v_max3_f32 v90, v90, v49, v50
	v_max3_f32 v90, v90, v51, v44
	v_max3_f32 v90, v90, v45, v46
	v_max3_f32 v90, v90, v47, v40
	v_max3_f32 v90, v90, v41, v42
	v_max_f32_e32 v90, v90, v43
	v_mov_b32_e32 v124, v90
	s_nop 1
	v_permlane16_swap_b32_e32 v124, v90
	v_max_f32_e32 v90, v90, v124
	v_mov_b32_e32 v124, v90
	s_nop 1
	v_permlane32_swap_b32_e32 v124, v90
	v_max3_f32 v127, v122, v90, v124
	v_sub_f32_e32 v90, v122, v127
	v_mov_b32_e32 v126, v127
	v_exp_f32_e32 v90, v90
	v_cmp_gt_f32_e32 vcc, v127, v122
	s_cbranch_vccz .Lnsa_fastq_norescale
	v_pk_mul_f32 v[38:39], v[38:39], v[90:91] op_sel_hi:[1,0]
	v_pk_mul_f32 v[36:37], v[36:37], v[90:91] op_sel_hi:[1,0]
	v_pk_mul_f32 v[34:35], v[34:35], v[90:91] op_sel_hi:[1,0]
	v_pk_mul_f32 v[32:33], v[32:33], v[90:91] op_sel_hi:[1,0]
	v_pk_mul_f32 v[30:31], v[30:31], v[90:91] op_sel_hi:[1,0]
	v_pk_mul_f32 v[28:29], v[28:29], v[90:91] op_sel_hi:[1,0]
	v_pk_mul_f32 v[26:27], v[26:27], v[90:91] op_sel_hi:[1,0]
	v_pk_mul_f32 v[24:25], v[24:25], v[90:91] op_sel_hi:[1,0]
.Lnsa_fastq_norescale:
	v_pk_add_f32 v[52:53], v[52:53], v[126:127] neg_lo:[0,1] neg_hi:[0,1]
	v_pk_add_f32 v[54:55], v[54:55], v[126:127] neg_lo:[0,1] neg_hi:[0,1]
	v_pk_add_f32 v[48:49], v[48:49], v[126:127] neg_lo:[0,1] neg_hi:[0,1]
	v_pk_add_f32 v[50:51], v[50:51], v[126:127] neg_lo:[0,1] neg_hi:[0,1]
	v_exp_f32_e32 v128, v52
	v_exp_f32_e32 v129, v53
	v_exp_f32_e32 v130, v54
	v_exp_f32_e32 v131, v55
	v_pk_add_f32 v[44:45], v[44:45], v[126:127] neg_lo:[0,1] neg_hi:[0,1]
	v_pk_add_f32 v[46:47], v[46:47], v[126:127] neg_lo:[0,1] neg_hi:[0,1]
	v_exp_f32_e32 v132, v48
	v_exp_f32_e32 v133, v49
	v_exp_f32_e32 v134, v50
	v_exp_f32_e32 v135, v51
	v_pk_add_f32 v[40:41], v[40:41], v[126:127] neg_lo:[0,1] neg_hi:[0,1]
	v_pk_add_f32 v[42:43], v[42:43], v[126:127] neg_lo:[0,1] neg_hi:[0,1]
	v_exp_f32_e32 v136, v44
	v_exp_f32_e32 v137, v45
	v_exp_f32_e32 v138, v46
	v_exp_f32_e32 v139, v47
	v_exp_f32_e32 v140, v40
	v_exp_f32_e32 v141, v41
	v_exp_f32_e32 v142, v42
	v_exp_f32_e32 v143, v43
	v_cvt_pk_bf16_f32 v248, v128, v129
	v_cvt_pk_bf16_f32 v249, v130, v131
	v_cvt_pk_bf16_f32 v250, v132, v133
	v_cvt_pk_bf16_f32 v251, v134, v135
	v_cvt_pk_bf16_f32 v52, v136, v137
	v_cvt_pk_bf16_f32 v53, v138, v139
	v_cvt_pk_bf16_f32 v54, v140, v141
	v_cvt_pk_bf16_f32 v55, v142, v143
	v_pk_add_f32 v[40:41], v[132:133], v[128:129]
	v_pk_add_f32 v[42:43], v[134:135], v[130:131]
	v_pk_add_f32 v[40:41], v[136:137], v[40:41]
	v_pk_add_f32 v[42:43], v[138:139], v[42:43]
	v_pk_add_f32 v[40:41], v[140:141], v[40:41]
	v_pk_add_f32 v[42:43], v[142:143], v[42:43]
	s_waitcnt lgkmcnt(4)
	v_mfma_f32_16x16x32_bf16 v[36:39], v[212:215], v[248:251], v[36:39]
	v_mfma_f32_16x16x32_bf16 v[32:35], v[216:219], v[248:251], v[32:35]
	v_mfma_f32_16x16x32_bf16 v[28:31], v[220:223], v[248:251], v[28:31]
	v_mfma_f32_16x16x32_bf16 v[24:27], v[224:227], v[248:251], v[24:27]
	s_waitcnt lgkmcnt(0)
	v_mfma_f32_16x16x32_bf16 v[36:39], v[232:235], v[52:55], v[36:39]
	v_add_f32_e32 v40, v40, v41
	v_mfma_f32_16x16x32_bf16 v[32:35], v[236:239], v[52:55], v[32:35]
	v_fmac_f32_e32 v40, v121, v90
	v_mfma_f32_16x16x32_bf16 v[28:31], v[240:243], v[52:55], v[28:31]
	v_add_f32_e32 v42, v42, v43
	v_mfma_f32_16x16x32_bf16 v[24:27], v[244:247], v[52:55], v[24:27]
	v_mov_b32_e32 v122, v127
	v_add_f32_e32 v121, v42, v40
	s_branch .Lnsa_fast_done
